# v11 + hand-written weight-conversion loop: two items of loads in flight per wave (software pipelined), ks scale applied after the LDS transpose, cvt_pk for the bf16 pack
# speedup vs baseline: 1.0060x; 1.0060x over previous
; __device__ __forceinline__ void tr_item(const float* W, int K, int N, const float* kscale, bf16* WT, int dst_row0, LAS float* scr, int k0, int n0, int lane) {
;     const int n4 = 4 * (lane & 7); const bool ok = (n0 + n4) < N;
; #pragma unroll
;     for (int i = 0; i < 8; ++i) { const int kk = 8 * i + (lane >> 3); f32x4 v = ok ? *(const f32x4*)(W + (size_t)(k0 + kk) * N + n0 + n4) : (f32x4){0.f, 0.f, 0.f, 0.f}; if (kscale) v = v * kscale[k0 + kk];
; __device__ __forceinline__ void prologue(const Args& a, LAS unsigned char* lds, int wave, int lane) {
;     ...
;     for (int it = gw; it < DEPTH * I_L; it += NGW) {
;         const int l = it / I_L; int r = it % I_L;
;         unsigned char* wl = ws + WS_W + (size_t)l * W_L;
;         if (r < 2 * I_W1) {
;             const bool second = r >= I_W1; if (second) r -= I_W1;
;             const float* W = a.in[second ? 14 : 2] + (size_t)l * D * NFF; const float* ks = a.in[second ? 13 : 1] + (size_t)l * D;
;             const int nblk = NFF / 32, kb = r / nblk, nb = r % nblk, n0 = 32 * nb;
;             const int dst = n0 < DFF ? (n0 / 128) * 256 + (n0 % 128) : ((n0 - DFF) / 128) * 256 + 128 + ((n0 - DFF) % 128);
;             tr_item(W, D, NFF, ks, (bf16*)(wl + (second ? W3_OFF : W1_OFF)), dst, scr, 64 * kb, n0, lane);
;             continue;
;         }
;         r -= 2 * I_W1;
;         if (r < 2 * I_W2) {
;             const bool second = r >= I_W2; if (second) r -= I_W2;
;             const float* W = a.in[second ? 15 : 3] + (size_t)l * DFF * D;
;             const int nblk = D / 32, kb = r / nblk, nb = r % nblk;
;             tr_item(W, DFF, D, nullptr, (bf16*)(wl + (second ? W4_OFF : W2_OFF)), 32 * nb, scr, 64 * kb, 32 * nb, lane);
;             continue;
;         }
;         r -= 2 * I_W2;
;         if (r < I_WIN) {
;             const float* W = a.in[5] + (size_t)l * D * INCOLS; const float* ks = a.in[4] + (size_t)l * D;
;             const int nblk = NPROJ / 32, kb = r / nblk, nb = r % nblk;
;             tr_item(W, D, INCOLS, ks, (bf16*)(wl + WIN_OFF), 32 * nb, scr, 64 * kb, 32 * nb, lane);
;             continue;
;         }
;         r -= I_WIN;
;         {
;             const float* W = a.in[12] + (size_t)l * D * D;
;             const int nblk = D / 32, kb = r / nblk, nb = r % nblk;
;             tr_item(W, D, D, nullptr, (bf16*)(wl + WOUT_OFF), 32 * nb, scr, 64 * kb, 32 * nb, lane);
;         }
.LBB0_11:
	s_load_dwordx16 s[36:51], s[0:1], 0x0
	s_load_dwordx16 s[12:27], s[0:1], 0x40
	v_readlane_b32 s0, v230, 4
	s_lshr_b32 s97, s0, 6
	s_cmp_lt_i32 s52, 1
	s_cselect_b64 s[0:1], -1, 0
	s_cmp_gt_i32 s53, 0
	s_cselect_b64 s[2:3], -1, 0
	s_and_b64 s[62:63], s[0:1], s[2:3]
	s_andn2_b64 vcc, exec, s[62:63]
	v_and_b32_e32 v200, 63, v201
	s_cbranch_vccnz .LBB0_98
	s_lshl_b32 s0, s10, 3
	s_add_i32 s11, s97, s0
	s_cmpk_gt_i32 s11, 0x50ff
	s_cbranch_scc1 .LBB0_81
	s_waitcnt lgkmcnt(0)
	v_lshrrev_b32_e32 v1, 3, v200
	v_and_b32_e32 v3, 7, v200
	v_lshlrev_b32_e32 v2, 4, v3
	v_lshlrev_b32_e32 v4, 5, v3
	s_lshl_b32 s0, s97, 14
	v_mul_u32_u24_e32 v6, 0x84, v1
	v_add3_u32 v6, v6, v2, s0
	v_add_u32_e32 v7, 0x420, v6
	v_add_u32_e32 v8, 0x420, v7
	v_add_u32_e32 v9, 0x420, v8
	v_add_u32_e32 v10, 0x420, v9
	v_add_u32_e32 v11, 0x420, v10
	v_add_u32_e32 v12, 0x420, v11
	v_add_u32_e32 v13, 0x420, v12
	v_mul_u32_u24_e32 v5, 0x420, v3
	v_lshl_add_u32 v5, v1, 2, v5
	v_add_u32_e32 v5, s0, v5
	v_lshlrev_b32_e32 v3, 2, v3
	s_mov_b32 s83, s11
	s_cmp_ge_u32 s83, 0x2880
	s_cselect_b32 s0, 1, 0
	s_mul_i32 s1, s0, 0x2880
	s_sub_u32 s1, s83, s1
	s_mul_i32 s2, s0, 0x2880000
	s_add_u32 s68, s34, s2
	s_addc_u32 s69, s35, 0
	s_add_u32 s68, s68, 0x800000
	s_addc_u32 s69, s69, 0
	s_mov_b32 s31, 64
	s_cmp_lt_u32 s1, 0x1600
	s_cbranch_scc1 .Lwq_t0_0
	s_cmp_lt_u32 s1, 0x2100
	s_cbranch_scc1 .Lwq_t1_0
	s_cmp_lt_u32 s1, 0x2680
	s_cbranch_scc1 .Lwq_t2_0
	s_sub_u32 s1, s1, 0x2680
	s_lshr_b32 s3, s1, 5
	s_and_b32 s4, s1, 31
	s_lshl_b32 s5, s0, 22
	s_lshl_b32 s86, s3, 18
	s_add_u32 s5, s5, s86
	s_lshl_b32 s86, s4, 7
	s_add_u32 s5, s5, s86
	s_add_u32 s64, s20, s5
	s_addc_u32 s65, s21, 0
	s_mov_b32 s29, 0x1000
	s_mov_b32 s66, s38
	s_mov_b32 s67, s39
	s_mov_b32 s71, 0
	s_lshl_b32 s5, s4, 16
	s_lshl_b32 s86, s3, 7
	s_add_u32 s5, s5, s86
	s_add_u32 s5, s5, 0x1600000
	s_add_u32 s68, s68, s5
	s_addc_u32 s69, s69, 0
	s_mov_b32 s70, 0x800
	s_branch .Lwq_te_0
.Lwq_t1_0:
	s_sub_u32 s1, s1, 0x1600
	s_cmp_ge_u32 s1, 0x580
	s_cselect_b32 s2, 1, 0
	s_mul_i32 s3, s2, 0x580
	s_sub_u32 s1, s1, s3
	s_cmp_eq_u32 s2, 0
	s_cselect_b32 s64, s42, s26
	s_cselect_b32 s65, s43, s27
	s_lshr_b32 s3, s1, 5
	s_and_b32 s4, s1, 31
	s_mul_i32 s5, s0, 0xb00000
	s_lshl_b32 s86, s3, 18
	s_add_u32 s5, s5, s86
	s_lshl_b32 s86, s4, 7
	s_add_u32 s5, s5, s86
	s_add_u32 s64, s64, s5
	s_addc_u32 s65, s65, 0
	s_mov_b32 s29, 0x1000
	s_mov_b32 s66, s38
	s_mov_b32 s67, s39
	s_mov_b32 s71, 0
	s_mul_i32 s5, s2, 0x1800000
	s_add_u32 s5, s5, 0xb00000
	s_mul_i32 s86, s4, 0x2c000
	s_add_u32 s5, s5, s86
	s_lshl_b32 s86, s3, 7
	s_add_u32 s5, s5, s86
	s_add_u32 s68, s68, s5
	s_addc_u32 s69, s69, 0
	s_mov_b32 s70, 0x1600
	s_branch .Lwq_te_0
.Lwq_t2_0:
	s_sub_u32 s1, s1, 0x2100
	s_mul_i32 s3, s1, 11916
	s_lshr_b32 s3, s3, 20
	s_mul_i32 s4, s3, 88
	s_sub_u32 s4, s1, s4
	s_mul_i32 s5, s0, 0xa10000
	s_mul_i32 s86, s3, 0xa1000
	s_add_u32 s5, s5, s86
	s_lshl_b32 s86, s4, 7
	s_add_u32 s5, s5, s86
	s_add_u32 s64, s46, s5
	s_addc_u32 s65, s47, 0
	s_mov_b32 s29, 0x2840
	s_lshl_b32 s5, s0, 12
	s_lshl_b32 s86, s3, 8
	s_add_u32 s5, s5, s86
	s_add_u32 s66, s44, s5
	s_addc_u32 s67, s45, 0
	s_mov_b32 s71, 1
	s_lshl_b32 s86, s4, 5
	s_sub_u32 s31, 0xa10, s86
	s_lshl_b32 s5, s4, 16
	s_lshl_b32 s86, s3, 7
	s_add_u32 s5, s5, s86
	s_add_u32 s5, s5, 0x1080000
	s_add_u32 s68, s68, s5
	s_addc_u32 s69, s69, 0
	s_mov_b32 s70, 0x800
	s_branch .Lwq_te_0
.Lwq_t0_0:
	s_cmp_ge_u32 s1, 0xb00
	s_cselect_b32 s2, 1, 0
	s_mul_i32 s3, s2, 0xb00
	s_sub_u32 s1, s1, s3
	s_cmp_eq_u32 s2, 0
	s_cselect_b32 s64, s40, s24
	s_cselect_b32 s65, s41, s25
	s_cselect_b32 s66, s38, s22
	s_cselect_b32 s67, s39, s23
	s_mul_i32 s3, s1, 5958
	s_lshr_b32 s3, s3, 20
	s_mul_i32 s4, s3, 176
	s_sub_u32 s4, s1, s4
	s_mul_i32 s5, s0, 0x1600000
	s_mul_i32 s86, s3, 0x160000
	s_add_u32 s5, s5, s86
	s_lshl_b32 s86, s4, 7
	s_add_u32 s5, s5, s86
	s_add_u32 s64, s64, s5
	s_addc_u32 s65, s65, 0
	s_mov_b32 s29, 0x5800
	s_lshl_b32 s5, s0, 12
	s_lshl_b32 s86, s3, 8
	s_add_u32 s5, s5, s86
	s_add_u32 s66, s66, s5
	s_addc_u32 s67, s67, 0
	s_mov_b32 s71, 1
	s_lshl_b32 s86, s4, 5
	s_cmp_ge_u32 s86, 0xb00
	s_cselect_b32 s87, 0xb00, 0
	s_cselect_b32 s88, 128, 0
	s_sub_u32 s86, s86, s87
	s_lshr_b32 s87, s86, 7
	s_lshl_b32 s87, s87, 8
	s_and_b32 s86, s86, 127
	s_add_u32 s86, s86, s87
	s_add_u32 s86, s86, s88
	s_mul_i32 s5, s2, 0x1800000
	s_lshl_b32 s86, s86, 11
	s_add_u32 s5, s5, s86
	s_lshl_b32 s86, s3, 7
	s_add_u32 s5, s5, s86
	s_add_u32 s68, s68, s5
	s_addc_u32 s69, s69, 0
	s_mov_b32 s70, 0x800
.Lwq_te_0:
	s_lshl_b32 s30, s29, 3
	v_mad_u32_u24 v14, v1, s29, v2
	s_cmp_lt_i32 s31, 32
	s_cbranch_scc0 .Lwq_nm_0
	v_cmp_gt_i32_e64 s[72:73], s31, v3
	s_or_b32 s71, s71, 2
	s_nop 2
	v_cndmask_b32_e64 v14, 0, v14, s[72:73]
; __device__ __forceinline__ void tr_item(const float* W, int K, int N, const float* kscale, bf16* WT, int dst_row0, LAS float* scr, int k0, int n0, int lane) {
;     const int n4 = 4 * (lane & 7); const bool ok = (n0 + n4) < N;
; #pragma unroll
;     for (int i = 0; i < 8; ++i) { const int kk = 8 * i + (lane >> 3); f32x4 v = ok ? *(const f32x4*)(W + (size_t)(k0 + kk) * N + n0 + n4) : (f32x4){0.f, 0.f, 0.f, 0.f}; if (kscale) v = v * kscale[k0 + kk];
; __device__ __forceinline__ void prologue(const Args& a, LAS unsigned char* lds, int wave, int lane) {
;     ...
;     for (int it = gw; it < DEPTH * I_L; it += NGW) {
;         const int l = it / I_L; int r = it % I_L;
;         unsigned char* wl = ws + WS_W + (size_t)l * W_L;
;         if (r < 2 * I_W1) {
;             const bool second = r >= I_W1; if (second) r -= I_W1;
;             const float* W = a.in[second ? 14 : 2] + (size_t)l * D * NFF; const float* ks = a.in[second ? 13 : 1] + (size_t)l * D;
;             const int nblk = NFF / 32, kb = r / nblk, nb = r % nblk, n0 = 32 * nb;
;             const int dst = n0 < DFF ? (n0 / 128) * 256 + (n0 % 128) : ((n0 - DFF) / 128) * 256 + 128 + ((n0 - DFF) % 128);
;             tr_item(W, D, NFF, ks, (bf16*)(wl + (second ? W3_OFF : W1_OFF)), dst, scr, 64 * kb, n0, lane);
;             continue;
;         }
;         r -= 2 * I_W1;
;         if (r < 2 * I_W2) {
;             const bool second = r >= I_W2; if (second) r -= I_W2;
;             const float* W = a.in[second ? 15 : 3] + (size_t)l * DFF * D;
;             const int nblk = D / 32, kb = r / nblk, nb = r % nblk;
;             tr_item(W, DFF, D, nullptr, (bf16*)(wl + (second ? W4_OFF : W2_OFF)), 32 * nb, scr, 64 * kb, 32 * nb, lane);
;             continue;
;         }
;         r -= 2 * I_W2;
;         if (r < I_WIN) {
;             const float* W = a.in[5] + (size_t)l * D * INCOLS; const float* ks = a.in[4] + (size_t)l * D;
;             const int nblk = NPROJ / 32, kb = r / nblk, nb = r % nblk;
;             tr_item(W, D, INCOLS, ks, (bf16*)(wl + WIN_OFF), 32 * nb, scr, 64 * kb, 32 * nb, lane);
;             continue;
;         }
;         r -= I_WIN;
;         {
;             const float* W = a.in[12] + (size_t)l * D * D;
;             const int nblk = D / 32, kb = r / nblk, nb = r % nblk;
;             tr_item(W, D, D, nullptr, (bf16*)(wl + WOUT_OFF), 32 * nb, scr, 64 * kb, 32 * nb, lane);
;         }
.Lwq_nm_0:
	v_add_u32_e32 v15, s30, v14
	v_add_u32_e32 v16, s30, v15
	v_add_u32_e32 v17, s30, v16
	v_add_u32_e32 v18, s30, v17
	v_add_u32_e32 v19, s30, v18
	v_add_u32_e32 v20, s30, v19
	v_add_u32_e32 v21, s30, v20
	global_load_dwordx4 v[80:83], v14, s[64:65]
	global_load_dwordx4 v[84:87], v15, s[64:65]
	global_load_dwordx4 v[88:91], v16, s[64:65]
	global_load_dwordx4 v[92:95], v17, s[64:65]
	global_load_dwordx4 v[96:99], v18, s[64:65]
	global_load_dwordx4 v[100:103], v19, s[64:65]
	global_load_dwordx4 v[104:107], v20, s[64:65]
	global_load_dwordx4 v[108:111], v21, s[64:65]
	global_load_dwordx4 v[112:115], v4, s[66:67]
	global_load_dwordx4 v[116:119], v4, s[66:67] offset:16
.Lwq_top0:
	s_lshl_b32 s82, s28, 3
	s_add_u32 s82, s83, s82
	s_cmp_lt_u32 s82, 0x5100
	s_cbranch_scc0 .Lwq_last0
	s_cmp_ge_u32 s82, 0x2880
	s_cselect_b32 s0, 1, 0
	s_mul_i32 s1, s0, 0x2880
	s_sub_u32 s1, s82, s1
	s_mul_i32 s2, s0, 0x2880000
	s_add_u32 s78, s34, s2
	s_addc_u32 s79, s35, 0
	s_add_u32 s78, s78, 0x800000
	s_addc_u32 s79, s79, 0
	s_mov_b32 s31, 64
	s_cmp_lt_u32 s1, 0x1600
	s_cbranch_scc1 .Lwq_t0_1
	s_cmp_lt_u32 s1, 0x2100
	s_cbranch_scc1 .Lwq_t1_1
	s_cmp_lt_u32 s1, 0x2680
	s_cbranch_scc1 .Lwq_t2_1
	s_sub_u32 s1, s1, 0x2680
	s_lshr_b32 s3, s1, 5
	s_and_b32 s4, s1, 31
	s_lshl_b32 s5, s0, 22
	s_lshl_b32 s86, s3, 18
	s_add_u32 s5, s5, s86
	s_lshl_b32 s86, s4, 7
	s_add_u32 s5, s5, s86
	s_add_u32 s74, s20, s5
	s_addc_u32 s75, s21, 0
	s_mov_b32 s29, 0x1000
	s_mov_b32 s76, s38
	s_mov_b32 s77, s39
	s_mov_b32 s81, 0
	s_lshl_b32 s5, s4, 16
	s_lshl_b32 s86, s3, 7
	s_add_u32 s5, s5, s86
	s_add_u32 s5, s5, 0x1600000
	s_add_u32 s78, s78, s5
	s_addc_u32 s79, s79, 0
	s_mov_b32 s80, 0x800
	s_branch .Lwq_te_1
.Lwq_t1_1:
	s_sub_u32 s1, s1, 0x1600
	s_cmp_ge_u32 s1, 0x580
	s_cselect_b32 s2, 1, 0
	s_mul_i32 s3, s2, 0x580
	s_sub_u32 s1, s1, s3
	s_cmp_eq_u32 s2, 0
	s_cselect_b32 s74, s42, s26
	s_cselect_b32 s75, s43, s27
	s_lshr_b32 s3, s1, 5
	s_and_b32 s4, s1, 31
	s_mul_i32 s5, s0, 0xb00000
	s_lshl_b32 s86, s3, 18
	s_add_u32 s5, s5, s86
	s_lshl_b32 s86, s4, 7
	s_add_u32 s5, s5, s86
	s_add_u32 s74, s74, s5
	s_addc_u32 s75, s75, 0
	s_mov_b32 s29, 0x1000
	s_mov_b32 s76, s38
	s_mov_b32 s77, s39
	s_mov_b32 s81, 0
	s_mul_i32 s5, s2, 0x1800000
	s_add_u32 s5, s5, 0xb00000
	s_mul_i32 s86, s4, 0x2c000
	s_add_u32 s5, s5, s86
	s_lshl_b32 s86, s3, 7
	s_add_u32 s5, s5, s86
	s_add_u32 s78, s78, s5
	s_addc_u32 s79, s79, 0
	s_mov_b32 s80, 0x1600
	s_branch .Lwq_te_1
.Lwq_t2_1:
	s_sub_u32 s1, s1, 0x2100
	s_mul_i32 s3, s1, 11916
	s_lshr_b32 s3, s3, 20
	s_mul_i32 s4, s3, 88
	s_sub_u32 s4, s1, s4
	s_mul_i32 s5, s0, 0xa10000
	s_mul_i32 s86, s3, 0xa1000
	s_add_u32 s5, s5, s86
	s_lshl_b32 s86, s4, 7
	s_add_u32 s5, s5, s86
	s_add_u32 s74, s46, s5
	s_addc_u32 s75, s47, 0
	s_mov_b32 s29, 0x2840
	s_lshl_b32 s5, s0, 12
	s_lshl_b32 s86, s3, 8
	s_add_u32 s5, s5, s86
	s_add_u32 s76, s44, s5
	s_addc_u32 s77, s45, 0
	s_mov_b32 s81, 1
	s_lshl_b32 s86, s4, 5
	s_sub_u32 s31, 0xa10, s86
	s_lshl_b32 s5, s4, 16
	s_lshl_b32 s86, s3, 7
	s_add_u32 s5, s5, s86
	s_add_u32 s5, s5, 0x1080000
	s_add_u32 s78, s78, s5
	s_addc_u32 s79, s79, 0
	s_mov_b32 s80, 0x800
	s_branch .Lwq_te_1
.Lwq_t0_1:
	s_cmp_ge_u32 s1, 0xb00
	s_cselect_b32 s2, 1, 0
	s_mul_i32 s3, s2, 0xb00
	s_sub_u32 s1, s1, s3
	s_cmp_eq_u32 s2, 0
	s_cselect_b32 s74, s40, s24
	s_cselect_b32 s75, s41, s25
	s_cselect_b32 s76, s38, s22
	s_cselect_b32 s77, s39, s23
	s_mul_i32 s3, s1, 5958
	s_lshr_b32 s3, s3, 20
	s_mul_i32 s4, s3, 176
	s_sub_u32 s4, s1, s4
	s_mul_i32 s5, s0, 0x1600000
	s_mul_i32 s86, s3, 0x160000
	s_add_u32 s5, s5, s86
	s_lshl_b32 s86, s4, 7
	s_add_u32 s5, s5, s86
	s_add_u32 s74, s74, s5
	s_addc_u32 s75, s75, 0
	s_mov_b32 s29, 0x5800
	s_lshl_b32 s5, s0, 12
	s_lshl_b32 s86, s3, 8
	s_add_u32 s5, s5, s86
	s_add_u32 s76, s76, s5
	s_addc_u32 s77, s77, 0
	s_mov_b32 s81, 1
	s_lshl_b32 s86, s4, 5
	s_cmp_ge_u32 s86, 0xb00
	s_cselect_b32 s87, 0xb00, 0
	s_cselect_b32 s88, 128, 0
	s_sub_u32 s86, s86, s87
	s_lshr_b32 s87, s86, 7
	s_lshl_b32 s87, s87, 8
	s_and_b32 s86, s86, 127
	s_add_u32 s86, s86, s87
	s_add_u32 s86, s86, s88
	s_mul_i32 s5, s2, 0x1800000
	s_lshl_b32 s86, s86, 11
	s_add_u32 s5, s5, s86
	s_lshl_b32 s86, s3, 7
	s_add_u32 s5, s5, s86
	s_add_u32 s78, s78, s5
	s_addc_u32 s79, s79, 0
	s_mov_b32 s80, 0x800
.Lwq_te_1:
	s_lshl_b32 s30, s29, 3
	v_mad_u32_u24 v14, v1, s29, v2
	s_cmp_lt_i32 s31, 32
	s_cbranch_scc0 .Lwq_nm_1
	v_cmp_gt_i32_e64 s[84:85], s31, v3
	s_or_b32 s81, s81, 2
	s_nop 2
	v_cndmask_b32_e64 v14, 0, v14, s[84:85]
.Lwq_nm_1:
	v_add_u32_e32 v15, s30, v14
	v_add_u32_e32 v16, s30, v15
	v_add_u32_e32 v17, s30, v16
	v_add_u32_e32 v18, s30, v17
	v_add_u32_e32 v19, s30, v18
	v_add_u32_e32 v20, s30, v19
	v_add_u32_e32 v21, s30, v20
	global_load_dwordx4 v[120:123], v14, s[74:75]
	global_load_dwordx4 v[124:127], v15, s[74:75]
	global_load_dwordx4 v[128:131], v16, s[74:75]
	global_load_dwordx4 v[132:135], v17, s[74:75]
	global_load_dwordx4 v[136:139], v18, s[74:75]
	global_load_dwordx4 v[140:143], v19, s[74:75]
	global_load_dwordx4 v[144:147], v20, s[74:75]
	global_load_dwordx4 v[148:151], v21, s[74:75]
	global_load_dwordx4 v[152:155], v4, s[76:77]
	global_load_dwordx4 v[156:159], v4, s[76:77] offset:16
	s_waitcnt vmcnt(10)
	s_branch .Lwq_proc0

; #define LAS __attribute__((address_space(3)))
; #define LDS_WAIT() asm volatile("s_waitcnt lgkmcnt(0)" ::: "memory")
; __device__ __forceinline__ unsigned pk2(float lo, float hi) { return f2bf(lo) | (f2bf(hi) << 16); }
; __device__ __forceinline__ void tr_item(const float* W, int K, int N, const float* kscale, bf16* WT, int dst_row0, LAS float* scr, int k0, int n0, int lane) {
;     ...
;     for (int i = 0; i < 8; ++i) { const int kk = 8 * i + (lane >> 3); f32x4 v = ok ? *(const f32x4*)(W + (size_t)(k0 + kk) * N + n0 + n4) : (f32x4){0.f, 0.f, 0.f, 0.f}; if (kscale) v = v * kscale[k0 + kk];
;         scr[kk * 33 + n4] = v[0]; scr[kk * 33 + n4 + 1] = v[1]; scr[kk * 33 + n4 + 2] = v[2]; scr[kk * 33 + n4 + 3] = v[3]; }
;     LDS_WAIT(); asm volatile("" ::: "memory");
;     const int c = lane & 7;
; #pragma unroll
;     for (int j = 0; j < 4; ++j) { const int n = (lane >> 3) + 8 * j; const LAS float* s = scr + (8 * c) * 33 + n;
;         u32x4 o; o.x = pk2(s[0 * 33], s[1 * 33]); o.y = pk2(s[2 * 33], s[3 * 33]); o.z = pk2(s[4 * 33], s[5 * 33]); o.w = pk2(s[6 * 33], s[7 * 33]);
;         *(u32x4*)(WT + (size_t)(dst_row0 + n) * K + k0 + 8 * c) = o; }
;     LDS_WAIT(); asm volatile("" ::: "memory");
; __device__ __forceinline__ void prologue(const Args& a, LAS unsigned char* lds, int wave, int lane) {
;     ...
;     for (int it = gw; it < DEPTH * I_L; it += NGW) {
;         const int l = it / I_L; int r = it % I_L;
.Lwq_proc0:
	s_bitcmp1_b32 s71, 1
	s_cbranch_scc0 .Lwq_bnm_2
	v_cndmask_b32_e64 v80, 0, v80, s[72:73]
	v_cndmask_b32_e64 v81, 0, v81, s[72:73]
	v_cndmask_b32_e64 v82, 0, v82, s[72:73]
	v_cndmask_b32_e64 v83, 0, v83, s[72:73]
	v_cndmask_b32_e64 v84, 0, v84, s[72:73]
	v_cndmask_b32_e64 v85, 0, v85, s[72:73]
	v_cndmask_b32_e64 v86, 0, v86, s[72:73]
	v_cndmask_b32_e64 v87, 0, v87, s[72:73]
	v_cndmask_b32_e64 v88, 0, v88, s[72:73]
	v_cndmask_b32_e64 v89, 0, v89, s[72:73]
	v_cndmask_b32_e64 v90, 0, v90, s[72:73]
	v_cndmask_b32_e64 v91, 0, v91, s[72:73]
	v_cndmask_b32_e64 v92, 0, v92, s[72:73]
	v_cndmask_b32_e64 v93, 0, v93, s[72:73]
	v_cndmask_b32_e64 v94, 0, v94, s[72:73]
	v_cndmask_b32_e64 v95, 0, v95, s[72:73]
	v_cndmask_b32_e64 v96, 0, v96, s[72:73]
	v_cndmask_b32_e64 v97, 0, v97, s[72:73]
	v_cndmask_b32_e64 v98, 0, v98, s[72:73]
	v_cndmask_b32_e64 v99, 0, v99, s[72:73]
	v_cndmask_b32_e64 v100, 0, v100, s[72:73]
	v_cndmask_b32_e64 v101, 0, v101, s[72:73]
	v_cndmask_b32_e64 v102, 0, v102, s[72:73]
	v_cndmask_b32_e64 v103, 0, v103, s[72:73]
	v_cndmask_b32_e64 v104, 0, v104, s[72:73]
	v_cndmask_b32_e64 v105, 0, v105, s[72:73]
	v_cndmask_b32_e64 v106, 0, v106, s[72:73]
	v_cndmask_b32_e64 v107, 0, v107, s[72:73]
	v_cndmask_b32_e64 v108, 0, v108, s[72:73]
	v_cndmask_b32_e64 v109, 0, v109, s[72:73]
	v_cndmask_b32_e64 v110, 0, v110, s[72:73]
	v_cndmask_b32_e64 v111, 0, v111, s[72:73]
.Lwq_bnm_2:
	ds_write2_b32 v6, v80, v81 offset1:1
	ds_write2_b32 v6, v82, v83 offset0:2 offset1:3
	ds_write2_b32 v7, v84, v85 offset1:1
	ds_write2_b32 v7, v86, v87 offset0:2 offset1:3
	ds_write2_b32 v8, v88, v89 offset1:1
	ds_write2_b32 v8, v90, v91 offset0:2 offset1:3
	ds_write2_b32 v9, v92, v93 offset1:1
	ds_write2_b32 v9, v94, v95 offset0:2 offset1:3
	ds_write2_b32 v10, v96, v97 offset1:1
	ds_write2_b32 v10, v98, v99 offset0:2 offset1:3
	ds_write2_b32 v11, v100, v101 offset1:1
	ds_write2_b32 v11, v102, v103 offset0:2 offset1:3
	ds_write2_b32 v12, v104, v105 offset1:1
	ds_write2_b32 v12, v106, v107 offset0:2 offset1:3
	ds_write2_b32 v13, v108, v109 offset1:1
	ds_write2_b32 v13, v110, v111 offset0:2 offset1:3
	s_waitcnt lgkmcnt(0)
	ds_read2_b32 v[26:27], v5 offset0:0 offset1:8
	ds_read2_b32 v[28:29], v5 offset0:33 offset1:41
	ds_read2_b32 v[30:31], v5 offset0:66 offset1:74
	ds_read2_b32 v[32:33], v5 offset0:99 offset1:107
	ds_read2_b32 v[34:35], v5 offset0:132 offset1:140
	ds_read2_b32 v[36:37], v5 offset0:165 offset1:173
	ds_read2_b32 v[38:39], v5 offset0:198 offset1:206
	ds_read2_b32 v[40:41], v5 offset0:231 offset1:239
	ds_read2_b32 v[42:43], v5 offset0:16 offset1:24
	ds_read2_b32 v[44:45], v5 offset0:49 offset1:57
	ds_read2_b32 v[46:47], v5 offset0:82 offset1:90
	ds_read2_b32 v[48:49], v5 offset0:115 offset1:123
	ds_read2_b32 v[50:51], v5 offset0:148 offset1:156
	ds_read2_b32 v[52:53], v5 offset0:181 offset1:189
	ds_read2_b32 v[54:55], v5 offset0:214 offset1:222
	ds_read2_b32 v[56:57], v5 offset0:247 offset1:255
	v_mad_u32_u24 v22, v1, s70, v2
	s_lshl_b32 s87, s70, 3
	v_add_u32_e32 v23, s87, v22
	v_add_u32_e32 v24, s87, v23
	v_add_u32_e32 v25, s87, v24
	s_waitcnt lgkmcnt(0)
	s_bitcmp1_b32 s71, 0
	s_cbranch_scc0 .Lwq_nks_2
	v_mul_f32_e32 v26, v26, v112
	v_mul_f32_e32 v27, v27, v112
	v_mul_f32_e32 v28, v28, v113
	v_mul_f32_e32 v29, v29, v113
	v_mul_f32_e32 v30, v30, v114
	v_mul_f32_e32 v31, v31, v114
	v_mul_f32_e32 v32, v32, v115
	v_mul_f32_e32 v33, v33, v115
	v_mul_f32_e32 v34, v34, v116
	v_mul_f32_e32 v35, v35, v116
	v_mul_f32_e32 v36, v36, v117
	v_mul_f32_e32 v37, v37, v117
	v_mul_f32_e32 v38, v38, v118
	v_mul_f32_e32 v39, v39, v118
	v_mul_f32_e32 v40, v40, v119
	v_mul_f32_e32 v41, v41, v119
	v_mul_f32_e32 v42, v42, v112
	v_mul_f32_e32 v43, v43, v112
	v_mul_f32_e32 v44, v44, v113
	v_mul_f32_e32 v45, v45, v113
	v_mul_f32_e32 v46, v46, v114
	v_mul_f32_e32 v47, v47, v114
	v_mul_f32_e32 v48, v48, v115
	v_mul_f32_e32 v49, v49, v115
	v_mul_f32_e32 v50, v50, v116
	v_mul_f32_e32 v51, v51, v116
	v_mul_f32_e32 v52, v52, v117
	v_mul_f32_e32 v53, v53, v117
	v_mul_f32_e32 v54, v54, v118
	v_mul_f32_e32 v55, v55, v118
	v_mul_f32_e32 v56, v56, v119
	v_mul_f32_e32 v57, v57, v119
.Lwq_nks_2:
	v_cvt_pk_bf16_f32 v58, v26, v28
	v_cvt_pk_bf16_f32 v59, v30, v32
	v_cvt_pk_bf16_f32 v60, v34, v36
	v_cvt_pk_bf16_f32 v61, v38, v40
	v_cvt_pk_bf16_f32 v62, v27, v29
	v_cvt_pk_bf16_f32 v63, v31, v33
	v_cvt_pk_bf16_f32 v64, v35, v37
	v_cvt_pk_bf16_f32 v65, v39, v41
	v_cvt_pk_bf16_f32 v66, v42, v44
	v_cvt_pk_bf16_f32 v67, v46, v48
	v_cvt_pk_bf16_f32 v68, v50, v52
	v_cvt_pk_bf16_f32 v69, v54, v56
	v_cvt_pk_bf16_f32 v70, v43, v45
	v_cvt_pk_bf16_f32 v71, v47, v49
	v_cvt_pk_bf16_f32 v72, v51, v53
	v_cvt_pk_bf16_f32 v73, v55, v57
	global_store_dwordx4 v22, v[58:61], s[68:69]
	global_store_dwordx4 v23, v[62:65], s[68:69]
	global_store_dwordx4 v24, v[66:69], s[68:69]
	global_store_dwordx4 v25, v[70:73], s[68:69]
	s_cmp_lt_u32 s82, 0x5100
	s_cbranch_scc0 .LBB0_81
	s_mov_b32 s83, s82
.Lwq_top1:
	s_lshl_b32 s82, s28, 3
	s_add_u32 s82, s83, s82
	s_cmp_lt_u32 s82, 0x5100
	s_cbranch_scc0 .Lwq_last1
	s_cmp_ge_u32 s82, 0x2880
	s_cselect_b32 s0, 1, 0
	s_mul_i32 s1, s0, 0x2880
	s_sub_u32 s1, s82, s1
	s_mul_i32 s2, s0, 0x2880000
	s_add_u32 s68, s34, s2
	s_addc_u32 s69, s35, 0
	s_add_u32 s68, s68, 0x800000
	s_addc_u32 s69, s69, 0
	s_mov_b32 s31, 64
	s_cmp_lt_u32 s1, 0x1600
	s_cbranch_scc1 .Lwq_t0_3
	s_cmp_lt_u32 s1, 0x2100
	s_cbranch_scc1 .Lwq_t1_3
	s_cmp_lt_u32 s1, 0x2680
	s_cbranch_scc1 .Lwq_t2_3
	s_sub_u32 s1, s1, 0x2680
	s_lshr_b32 s3, s1, 5
	s_and_b32 s4, s1, 31
	s_lshl_b32 s5, s0, 22
	s_lshl_b32 s86, s3, 18
	s_add_u32 s5, s5, s86
	s_lshl_b32 s86, s4, 7
	s_add_u32 s5, s5, s86
	s_add_u32 s64, s20, s5
	s_addc_u32 s65, s21, 0
	s_mov_b32 s29, 0x1000
	s_mov_b32 s66, s38
	s_mov_b32 s67, s39
	s_mov_b32 s71, 0
	s_lshl_b32 s5, s4, 16
	s_lshl_b32 s86, s3, 7
	s_add_u32 s5, s5, s86
	s_add_u32 s5, s5, 0x1600000
	s_add_u32 s68, s68, s5
	s_addc_u32 s69, s69, 0
	s_mov_b32 s70, 0x800
	s_branch .Lwq_te_3

; __device__ __forceinline__ void tr_item(const float* W, int K, int N, const float* kscale, bf16* WT, int dst_row0, LAS float* scr, int k0, int n0, int lane) {
;     const int n4 = 4 * (lane & 7); const bool ok = (n0 + n4) < N;
; #pragma unroll
;     for (int i = 0; i < 8; ++i) { const int kk = 8 * i + (lane >> 3); f32x4 v = ok ? *(const f32x4*)(W + (size_t)(k0 + kk) * N + n0 + n4) : (f32x4){0.f, 0.f, 0.f, 0.f}; if (kscale) v = v * kscale[k0 + kk];
.Lwq_nm_3:
	v_add_u32_e32 v15, s30, v14
	v_add_u32_e32 v16, s30, v15
	v_add_u32_e32 v17, s30, v16
	v_add_u32_e32 v18, s30, v17
	v_add_u32_e32 v19, s30, v18
	v_add_u32_e32 v20, s30, v19
	v_add_u32_e32 v21, s30, v20
	global_load_dwordx4 v[80:83], v14, s[64:65]
	global_load_dwordx4 v[84:87], v15, s[64:65]
	global_load_dwordx4 v[88:91], v16, s[64:65]
	global_load_dwordx4 v[92:95], v17, s[64:65]
	global_load_dwordx4 v[96:99], v18, s[64:65]
	global_load_dwordx4 v[100:103], v19, s[64:65]
	global_load_dwordx4 v[104:107], v20, s[64:65]
	global_load_dwordx4 v[108:111], v21, s[64:65]
	global_load_dwordx4 v[112:115], v4, s[66:67]
	global_load_dwordx4 v[116:119], v4, s[66:67] offset:16
	s_waitcnt vmcnt(10)
	s_branch .Lwq_proc1

; #define LAS __attribute__((address_space(3)))
; #define LDS_WAIT() asm volatile("s_waitcnt lgkmcnt(0)" ::: "memory")
; __device__ __forceinline__ unsigned pk2(float lo, float hi) { return f2bf(lo) | (f2bf(hi) << 16); }
; __device__ __forceinline__ void tr_item(const float* W, int K, int N, const float* kscale, bf16* WT, int dst_row0, LAS float* scr, int k0, int n0, int lane) {
;     ...
;     for (int i = 0; i < 8; ++i) { const int kk = 8 * i + (lane >> 3); f32x4 v = ok ? *(const f32x4*)(W + (size_t)(k0 + kk) * N + n0 + n4) : (f32x4){0.f, 0.f, 0.f, 0.f}; if (kscale) v = v * kscale[k0 + kk];
;         scr[kk * 33 + n4] = v[0]; scr[kk * 33 + n4 + 1] = v[1]; scr[kk * 33 + n4 + 2] = v[2]; scr[kk * 33 + n4 + 3] = v[3]; }
;     LDS_WAIT(); asm volatile("" ::: "memory");
;     const int c = lane & 7;
; #pragma unroll
;     for (int j = 0; j < 4; ++j) { const int n = (lane >> 3) + 8 * j; const LAS float* s = scr + (8 * c) * 33 + n;
;         u32x4 o; o.x = pk2(s[0 * 33], s[1 * 33]); o.y = pk2(s[2 * 33], s[3 * 33]); o.z = pk2(s[4 * 33], s[5 * 33]); o.w = pk2(s[6 * 33], s[7 * 33]);
;         *(u32x4*)(WT + (size_t)(dst_row0 + n) * K + k0 + 8 * c) = o; }
;     LDS_WAIT(); asm volatile("" ::: "memory");
.Lwq_proc1:
	s_bitcmp1_b32 s81, 1
	s_cbranch_scc0 .Lwq_bnm_4
	v_cndmask_b32_e64 v120, 0, v120, s[84:85]
	v_cndmask_b32_e64 v121, 0, v121, s[84:85]
	v_cndmask_b32_e64 v122, 0, v122, s[84:85]
	v_cndmask_b32_e64 v123, 0, v123, s[84:85]
	v_cndmask_b32_e64 v124, 0, v124, s[84:85]
	v_cndmask_b32_e64 v125, 0, v125, s[84:85]
	v_cndmask_b32_e64 v126, 0, v126, s[84:85]
	v_cndmask_b32_e64 v127, 0, v127, s[84:85]
	v_cndmask_b32_e64 v128, 0, v128, s[84:85]
	v_cndmask_b32_e64 v129, 0, v129, s[84:85]
	v_cndmask_b32_e64 v130, 0, v130, s[84:85]
	v_cndmask_b32_e64 v131, 0, v131, s[84:85]
	v_cndmask_b32_e64 v132, 0, v132, s[84:85]
	v_cndmask_b32_e64 v133, 0, v133, s[84:85]
	v_cndmask_b32_e64 v134, 0, v134, s[84:85]
	v_cndmask_b32_e64 v135, 0, v135, s[84:85]
	v_cndmask_b32_e64 v136, 0, v136, s[84:85]
	v_cndmask_b32_e64 v137, 0, v137, s[84:85]
	v_cndmask_b32_e64 v138, 0, v138, s[84:85]
	v_cndmask_b32_e64 v139, 0, v139, s[84:85]
	v_cndmask_b32_e64 v140, 0, v140, s[84:85]
	v_cndmask_b32_e64 v141, 0, v141, s[84:85]
	v_cndmask_b32_e64 v142, 0, v142, s[84:85]
	v_cndmask_b32_e64 v143, 0, v143, s[84:85]
	v_cndmask_b32_e64 v144, 0, v144, s[84:85]
	v_cndmask_b32_e64 v145, 0, v145, s[84:85]
	v_cndmask_b32_e64 v146, 0, v146, s[84:85]
	v_cndmask_b32_e64 v147, 0, v147, s[84:85]
	v_cndmask_b32_e64 v148, 0, v148, s[84:85]
	v_cndmask_b32_e64 v149, 0, v149, s[84:85]
	v_cndmask_b32_e64 v150, 0, v150, s[84:85]
	v_cndmask_b32_e64 v151, 0, v151, s[84:85]
.Lwq_bnm_4:
	ds_write2_b32 v6, v120, v121 offset1:1
	ds_write2_b32 v6, v122, v123 offset0:2 offset1:3
	ds_write2_b32 v7, v124, v125 offset1:1
	ds_write2_b32 v7, v126, v127 offset0:2 offset1:3
	ds_write2_b32 v8, v128, v129 offset1:1
	ds_write2_b32 v8, v130, v131 offset0:2 offset1:3
	ds_write2_b32 v9, v132, v133 offset1:1
	ds_write2_b32 v9, v134, v135 offset0:2 offset1:3
	ds_write2_b32 v10, v136, v137 offset1:1
	ds_write2_b32 v10, v138, v139 offset0:2 offset1:3
	ds_write2_b32 v11, v140, v141 offset1:1
	ds_write2_b32 v11, v142, v143 offset0:2 offset1:3
	ds_write2_b32 v12, v144, v145 offset1:1
	ds_write2_b32 v12, v146, v147 offset0:2 offset1:3
	ds_write2_b32 v13, v148, v149 offset1:1
	ds_write2_b32 v13, v150, v151 offset0:2 offset1:3
	s_waitcnt lgkmcnt(0)
	ds_read2_b32 v[26:27], v5 offset0:0 offset1:8
	ds_read2_b32 v[28:29], v5 offset0:33 offset1:41
	ds_read2_b32 v[30:31], v5 offset0:66 offset1:74
	ds_read2_b32 v[32:33], v5 offset0:99 offset1:107
	ds_read2_b32 v[34:35], v5 offset0:132 offset1:140
	ds_read2_b32 v[36:37], v5 offset0:165 offset1:173
	ds_read2_b32 v[38:39], v5 offset0:198 offset1:206
	ds_read2_b32 v[40:41], v5 offset0:231 offset1:239
	ds_read2_b32 v[42:43], v5 offset0:16 offset1:24
	ds_read2_b32 v[44:45], v5 offset0:49 offset1:57
	ds_read2_b32 v[46:47], v5 offset0:82 offset1:90
	ds_read2_b32 v[48:49], v5 offset0:115 offset1:123
	ds_read2_b32 v[50:51], v5 offset0:148 offset1:156
	ds_read2_b32 v[52:53], v5 offset0:181 offset1:189
	ds_read2_b32 v[54:55], v5 offset0:214 offset1:222
	ds_read2_b32 v[56:57], v5 offset0:247 offset1:255
	v_mad_u32_u24 v22, v1, s80, v2
	s_lshl_b32 s87, s80, 3
	v_add_u32_e32 v23, s87, v22
	v_add_u32_e32 v24, s87, v23
	v_add_u32_e32 v25, s87, v24
	s_waitcnt lgkmcnt(0)
	s_bitcmp1_b32 s81, 0
	s_cbranch_scc0 .Lwq_nks_4
	v_mul_f32_e32 v26, v26, v152
	v_mul_f32_e32 v27, v27, v152
	v_mul_f32_e32 v28, v28, v153
	v_mul_f32_e32 v29, v29, v153
	v_mul_f32_e32 v30, v30, v154
	v_mul_f32_e32 v31, v31, v154
	v_mul_f32_e32 v32, v32, v155
	v_mul_f32_e32 v33, v33, v155
	v_mul_f32_e32 v34, v34, v156
	v_mul_f32_e32 v35, v35, v156
	v_mul_f32_e32 v36, v36, v157
	v_mul_f32_e32 v37, v37, v157
	v_mul_f32_e32 v38, v38, v158
	v_mul_f32_e32 v39, v39, v158
	v_mul_f32_e32 v40, v40, v159
	v_mul_f32_e32 v41, v41, v159
	v_mul_f32_e32 v42, v42, v152
	v_mul_f32_e32 v43, v43, v152
	v_mul_f32_e32 v44, v44, v153
	v_mul_f32_e32 v45, v45, v153
	v_mul_f32_e32 v46, v46, v154
	v_mul_f32_e32 v47, v47, v154
	v_mul_f32_e32 v48, v48, v155
	v_mul_f32_e32 v49, v49, v155
	v_mul_f32_e32 v50, v50, v156
	v_mul_f32_e32 v51, v51, v156
	v_mul_f32_e32 v52, v52, v157
	v_mul_f32_e32 v53, v53, v157
	v_mul_f32_e32 v54, v54, v158
	v_mul_f32_e32 v55, v55, v158
	v_mul_f32_e32 v56, v56, v159
	v_mul_f32_e32 v57, v57, v159
.Lwq_nks_4:
	v_cvt_pk_bf16_f32 v58, v26, v28
	v_cvt_pk_bf16_f32 v59, v30, v32
	v_cvt_pk_bf16_f32 v60, v34, v36
	v_cvt_pk_bf16_f32 v61, v38, v40
	v_cvt_pk_bf16_f32 v62, v27, v29
	v_cvt_pk_bf16_f32 v63, v31, v33
	v_cvt_pk_bf16_f32 v64, v35, v37
	v_cvt_pk_bf16_f32 v65, v39, v41
	v_cvt_pk_bf16_f32 v66, v42, v44
	v_cvt_pk_bf16_f32 v67, v46, v48
	v_cvt_pk_bf16_f32 v68, v50, v52
	v_cvt_pk_bf16_f32 v69, v54, v56
	v_cvt_pk_bf16_f32 v70, v43, v45
	v_cvt_pk_bf16_f32 v71, v47, v49
	v_cvt_pk_bf16_f32 v72, v51, v53
	v_cvt_pk_bf16_f32 v73, v55, v57
	global_store_dwordx4 v22, v[58:61], s[78:79]
	global_store_dwordx4 v23, v[62:65], s[78:79]
	global_store_dwordx4 v24, v[66:69], s[78:79]
	global_store_dwordx4 v25, v[70:73], s[78:79]
	s_cmp_lt_u32 s82, 0x5100
	s_cbranch_scc0 .LBB0_81
	s_mov_b32 s83, s82
	s_branch .Lwq_top0
